# MLA K/V fragment prefetch, padded so later code keeps baseline addresses
# speedup vs baseline: 1.0020x; 1.0020x over previous
.LBB0_793:
	s_nop 0
	s_nop 0
	s_nop 0
	s_nop 0
	s_nop 0
	s_and_b32 s2, s4, 0x7f
	s_lshl_b32 s3, s2, 3
	v_readlane_b32 s5, v250, 0
	s_add_i32 s3, s3, s5
	v_mov_b32_e32 v64, 0x4400
	v_mad_u64_u32 v[134:135], s[6:7], s3, v64, v[154:155]
	s_cmpk_gt_u32 s4, 0x7f
	s_mov_b64 s[8:9], -1
	s_cbranch_scc0 .LBB0_801
	v_readlane_b32 s6, v250, 15
	v_readlane_b32 s7, v250, 16
	s_andn2_b64 vcc, exec, s[6:7]
	s_cbranch_vccnz .LBB0_800
	s_lshl_b32 s2, s2, 6
	v_readlane_b32 s3, v252, 21
	s_add_u32 s8, s3, s2
	v_readlane_b32 s2, v252, 22
	s_addc_u32 s9, s2, 0
	s_mov_b32 s2, 0x100001
	s_branch .LBB0_797
